# v7 plus conflict-free LDS swizzle for the attention K tiles (row&15 for 256B rows, (row>>1)&7 for 128B and 384B rows) on both the DMA and read sides
# speedup vs baseline: 1.0042x; 1.0042x over previous
; template <int DK, int MODE> ...
;     const int tid = opaque_tid(), wid = __builtin_amdgcn_readfirstlane(tid >> 6), lane = tid & 63, r32 = lane & 31, hi = lane >> 5;
;     constexpr int PITCH = DK * 2, CPR = DK / 8, NKC = (64 * CPR) / 512, SHM_K = 64 * PITCH, ND = DK / 16;
;     LAS char* V_lds = lds; LAS char* K_lds = lds + OFF_K; LAS float* fk_l = (LAS float*)(lds + OFF_FK); LAS float* ws = (LAS float*)(lds + OFF_WS) + wid * 64;
;     bf16x8 qr[ND];
; #pragma unroll
;     for (int d0 = 0; d0 < ND; ++d0) qr[d0] = *(const GAS bf16x8*)(Qw + (size_t)r32 * qpitch + d0 * 16 + hi * 8);
;     constexpr int NKI = (64 * PITCH) / 8192;
;     const GAS bf16_t* kp[NKI]; int kstep[NKI];
; #pragma unroll
;     for (int i = 0; i < NKI; ++i) { const int off = (wid * NKI + i) * 1024 + lane * 16, row = off / PITCH, rem = off % PITCH, p = rem >> 4, ch = (p & ~7) | ((p & 7) ^ (row & 7));
;         if (DK <= 128 || ch < 16) { kp[i] = (const GAS bf16_t*)Kb + (size_t)row * kpitch + ch * 8; kstep[i] = 64 * kpitch; }
;         else { kp[i] = (const GAS bf16_t*)Kb2 + (size_t)row * k2pitch + (ch - 16) * 8; kstep[i] = 64 * k2pitch; } }
;     const GAS bf16_t* vp[2];
; #pragma unroll
;     for (int i = 0; i < 2; ++i) { const int off = (wid * 2 + i) * 1024 + lane * 16, sub = off >> 9, rem = off & 511, kk = (sub >> 2) * 8 + (rem >> 6), kq = (kk & ~0xC) | ((kk & 4) << 1) | ((kk & 8) >> 1), c = (sub & 3) * 32 + ((rem & 63) >> 1);
; __device__ __forceinline__ void ph_attn(const Args& a, char* lds, int l, int rep) {
;     ...
;     for (;;) {
;         if (tid == 0) ldsctl[0] = atomicAdd(ctr, 1u);
;         __syncthreads();
;         const int u = (int)ldsctl[0];
;         __syncthreads();
;         if (u >= 768) break;
;         const int qb = 7 - u / 96, within = u % 96, type = within >> 5, bh = within & 31, b = bh >> 2, h = bh & 3;
;         const size_t brow = (size_t)b * SEQ, qrow = brow + qb * 256 + wave * 32; const int qlo = qb * 256 + wave * 32, NT = 4 * (qb + 1);
;         f32x16 o[4];
;     ...
;         if (type == 2) {
;             const float* Fk = WSP(float, WS_CUMF) + (size_t)bh * SEQ;
;             att::attn_pass<128, 1>((LAS char*)lds, P + qrow * NIN + PC_FQ + h * 128, NIN, P + brow * NIN + PC_FK + h * 128, NIN, nullptr, 0, P + brow * NIN + PC_FV + h * 128, NIN,
;                                    Fk, Fk[qlo + r32], NT, qlo, 0.08838834764831845f * LOG2E, o);
.LBB0_864:
	s_or_b64 exec, exec, s[0:1]
	v_readlane_b32 s0, v255, 19
	s_waitcnt lgkmcnt(0)
	s_barrier
	v_mov_b32_e32 v0, s0
	ds_read_b32 v0, v0
	s_movk_i32 s0, 0x2ff
	s_waitcnt lgkmcnt(0)
	s_barrier
	v_cmp_lt_i32_e32 vcc, s0, v0
	v_readfirstlane_b32 s2, v0
	s_mov_b64 s[0:1], -1
	s_cbranch_vccnz .LBB0_861
	s_mul_hi_i32 s0, s2, 0xd5555555
	s_lshr_b32 s1, s0, 31
	s_ashr_i32 s0, s0, 4
	s_add_i32 s0, s0, s1
	s_mul_hi_i32 s1, s2, 0x2aaaaaab
	s_lshr_b32 s4, s1, 31
	s_lshr_b32 s1, s1, 4
	s_add_i32 s1, s1, s4
	s_mulk_i32 s1, 0x60
	s_sub_i32 s2, s2, s1
	s_lshl_b32 s1, s2, 9
	s_and_b32 s10, s1, 0x3800
	s_lshl_b32 s1, s0, 8
	v_writelane_b32 v255, s1, 53
	s_ashr_i32 s84, s2, 5
	s_and_b32 s86, s2, 3
	s_add_i32 s6, s1, 0x700
	v_readlane_b32 s5, v255, 51
	s_add_u32 s1, s6, s5
	v_readlane_b32 s4, v255, 44
	s_addc_u32 s4, 0, s4
	s_add_u32 s76, s1, s10
	s_addc_u32 s77, s4, 0
	s_lshl_b32 s4, s0, 2
	s_add_i32 s6, s6, s5
	s_add_i32 s7, s4, 32
	s_mov_b64 s[0:1], -1
	s_cmp_gt_i32 s84, 1
	v_writelane_b32 v255, s10, 54
	s_mul_i32 s16, s10, 0x2600
	s_cbranch_scc0 .LBB0_1010
	s_and_b32 s0, s2, 31
	s_lshl_b32 s0, s0, 13
	v_readlane_b32 s1, v255, 49
	s_add_u32 s10, s1, s0
	v_readlane_b32 s0, v255, 50
	s_addc_u32 s11, s0, 0
	s_mul_i32 s0, s77, 0x2600
	s_mul_hi_u32 s1, s76, 0x2600
	s_add_i32 s1, s1, s0
	s_mul_i32 s0, s76, 0x2600
	v_readlane_b32 s5, v255, 36
	s_add_u32 s0, s5, s0
	v_readlane_b32 s14, v255, 37
	s_addc_u32 s1, s14, s1
	s_lshl_b32 s85, s86, 7
	s_lshl_b32 s2, s86, 8
	s_add_u32 s12, s0, s2
	s_addc_u32 s13, s1, 0
	s_add_u32 s0, s5, s16
	s_addc_u32 s1, s14, 0
	v_or_b32_e32 v2, s6, v146
	s_add_u32 s5, s0, s2
	v_ashrrev_i32_e32 v3, 31, v2
	s_mov_b32 s93, s16
	s_addc_u32 s16, s1, 0
	v_lshl_add_u64 v[2:3], v[2:3], 2, s[10:11]
	v_mov_b32_e32 v22, v240
	s_add_u32 s14, s5, 0x400
	flat_load_dword v66, v[2:3]
	s_addc_u32 s15, s16, 0
	v_and_b32_e32 v24, 31, v22
	v_mul_u32_u24_e32 v0, 0x1300, v24
	s_add_u32 s0, s5, 0x800
	v_readfirstlane_b32 s2, v22
	v_lshlrev_b32_e32 v0, 1, v0
	s_addc_u32 s1, s16, 0
	v_and_b32_e32 v23, 63, v22
	v_bfe_u32 v25, v22, 5, 1
	v_lshl_add_u64 v[2:3], s[12:13], 0, v[0:1]
	s_lshl_b32 s12, s2, 5
	v_lshlrev_b32_e32 v0, 4, v25
	s_and_b32 s12, s12, 0xfffff800
	v_lshlrev_b32_e32 v26, 4, v23
	v_lshl_add_u64 v[2:3], v[2:3], 0, v[0:1]
	v_or_b32_e32 v8, s12, v26
	global_load_dwordx4 v[98:101], v[2:3], off
	global_load_dwordx4 v[102:105], v[2:3], off offset:32
	global_load_dwordx4 v[106:109], v[2:3], off offset:64
	global_load_dwordx4 v[110:113], v[2:3], off offset:96
	global_load_dwordx4 v[114:117], v[2:3], off offset:128
	global_load_dwordx4 v[118:121], v[2:3], off offset:160
	global_load_dwordx4 v[122:125], v[2:3], off offset:192
	global_load_dwordx4 v[126:129], v[2:3], off offset:224
	v_ashrrev_i32_e32 v2, 31, v8
	v_add_u32_sdwa v2, v8, v2 dst_sel:DWORD dst_unused:UNUSED_PAD src0_sel:DWORD src1_sel:BYTE_3
	v_ashrrev_i32_e32 v2, 8, v2
	s_bfe_i32 s13, s2, 0x1001a
	v_mul_i32_i24_e32 v3, 0x100, v2
	s_lshr_b32 s13, s13, 24
	v_sub_u32_e32 v3, v8, v3
	v_add_u32_e32 v8, s13, v8
	v_add_u32_e32 v8, 0x400, v8
	v_ashrrev_i32_e32 v9, 4, v3
	v_ashrrev_i32_e32 v8, 8, v8
	v_bitop3_b32 v6, v2, v9, 15 bitop3:0x6c
	v_mul_hi_i32_i24_e32 v3, 0x2600, v2
	v_mul_i32_i24_e32 v2, 0x2600, v2
	v_bitop3_b32 v12, v8, v9, 15 bitop3:0x6c
	v_mul_hi_i32_i24_e32 v9, 0x2600, v8
	v_mul_i32_i24_e32 v8, 0x2600, v8
	s_ashr_i32 s13, s12, 8
	v_lshrrev_b32_e32 v15, 1, v22
	v_lshl_add_u64 v[4:5], s[14:15], 0, v[2:3]
	v_lshlrev_b32_e32 v6, 3, v6
	v_lshl_add_u64 v[10:11], s[14:15], 0, v[8:9]
	v_bfe_u32 v14, v22, 2, 2
	s_and_b32 s14, s13, 0xfffff0
	v_and_b32_e32 v15, 8, v15
	v_ashrrev_i32_e32 v7, 31, v6
	v_lshlrev_b32_e32 v12, 3, v12
	s_lshr_b32 s13, s13, 1
	v_or3_b32 v14, v15, v14, s14
	v_lshlrev_b64 v[6:7], 1, v[6:7]
	v_ashrrev_i32_e32 v13, 31, v12
	v_lshlrev_b32_e32 v27, 3, v23
	v_and_or_b32 v14, s13, 4, v14
	v_and_b32_e32 v15, 32, v22
	s_add_i32 s88, s12, 0
	v_lshl_add_u64 v[4:5], v[4:5], 0, v[6:7]
	v_lshlrev_b64 v[12:13], 1, v[12:13]
	v_and_or_b32 v18, v27, 24, v15
	v_mul_hi_i32_i24_e32 v15, 0x2600, v14
	v_mul_i32_i24_e32 v14, 0x2600, v14
	s_add_i32 m0, s88, 0x8000
	v_lshl_add_u64 v[10:11], v[10:11], 0, v[12:13]
	v_lshl_add_u64 v[16:17], s[0:1], 0, v[14:15]
	v_lshlrev_b32_e32 v18, 1, v18
	v_mov_b32_e32 v19, v1
	global_load_lds_dwordx4 v[4:5], off
	s_add_i32 m0, s88, 0x8400
	v_lshl_add_u64 v[16:17], v[16:17], 0, v[18:19]
	global_load_lds_dwordx4 v[10:11], off
	s_mov_b32 m0, s88
	v_lshl_add_u64 v[20:21], v[16:17], 0, s[96:97]
	global_load_lds_dwordx4 v[16:17], off
	s_add_i32 m0, s88, 0x400
	s_add_i32 s12, 0, 0x14000
	global_load_lds_dwordx4 v[20:21], off
	v_lshlrev_b32_e32 v4, 2, v23
	s_mov_b32 m0, s12
	v_lshlrev_b32_e32 v5, 1, v22
	global_load_lds_dword v4, s[10:11]
	v_and_b32_e32 v11, 32, v5
	v_mov_b32_e32 v5, v1
	s_waitcnt vmcnt(0)
	v_lshl_add_u64 v[130:131], s[10:11], 0, v[4:5]
	v_lshlrev_b32_e32 v4, 4, v22
	s_movk_i32 s13, 0xf0
	v_and_b32_e32 v5, 0xf0, v4
	v_bitop3_b32 v166, v0, v4, s13 bitop3:0x78
	s_movk_i32 s13, 0x60
	v_bitop3_b32 v169, v0, v5, s13 bitop3:0x36
	s_movk_i32 s13, 0x80
	s_and_b32 s2, s2, 0x3fffffc0
	v_bitop3_b32 v170, v0, v5, s13 bitop3:0x36
	s_movk_i32 s13, 0xa0
	s_lshl_b32 s2, s2, 2
	v_bitop3_b32 v171, v0, v5, s13 bitop3:0x36
	s_movk_i32 s13, 0xc0
	s_add_i32 s89, s2, 0
	v_bitop3_b32 v172, v0, v5, s13 bitop3:0x36
	s_movk_i32 s13, 0xe0
	s_add_i32 s89, s89, 0x14200
	s_or_b32 s2, s6, 31
	v_bitop3_b32 v173, v0, v5, s13 bitop3:0x36
	s_movk_i32 s13, 0x118
	v_or_b32_e32 v14, v14, v18
	v_and_b32_e32 v10, 0xc0, v26
	v_and_or_b32 v4, v27, s13, v11
	v_lshl_add_u64 v[132:133], s[0:1], 0, v[14:15]
	s_add_u32 s0, s5, 0x98400
	v_bitop3_b32 v167, v0, v5, 32 bitop3:0x36
	v_bitop3_b32 v168, v0, v5, 64 bitop3:0x36
	v_add3_u32 v174, v10, 0, v4
	s_addc_u32 s1, s16, 0
	v_lshl_add_u64 v[4:5], v[8:9], 0, v[12:13]
	v_lshl_add_u64 v[2:3], v[2:3], 0, v[6:7]
	v_lshl_add_u64 v[134:135], s[0:1], 0, v[4:5]
	v_lshl_add_u64 v[136:137], s[0:1], 0, v[2:3]
	v_readlane_b32 s0, v255, 52
	v_readlane_b32 s1, v255, 53
	s_add_i32 s0, s0, s1
	s_waitcnt vmcnt(0) lgkmcnt(0)
	s_barrier
; __device__ __forceinline__ int v_rd_base(int lane) { return ((lane & 3) << 3) | (((lane >> 2) & 3) << 6) | (((lane >> 4) & 1) << 5) | (((lane >> 5) & 1) << 8); }
; template <int DK, int MODE> ...
;     ...
;     float m_reg = -1e30f, l_reg = 0.f;
; #pragma unroll
;     for (int d = 0; d < 4; ++d) o[d] = f32x16{};
;     const int vb00 = (int)(uintptr_t)V_lds + v_rd_base(lane);
;     A_LOAD(0, 0); asm volatile("s_waitcnt vmcnt(0) lgkmcnt(0)\n\ts_barrier" ::: "memory");
;     for (int t = 0; t < NT; ++t) {
;         const int buf = t & 1, kb = t * 64;
;         if (t + 1 < NT) A_LOAD(t + 1, buf ^ 1);
	v_lshlrev_b32_e32 v16, 2, v25
	v_add_u32_e32 v2, s0, v24
	v_mov_b32_e32 v34, v1
	v_mov_b32_e32 v35, v1
	v_mov_b32_e32 v48, v1
	v_mov_b32_e32 v49, v1
	v_lshl_add_u32 v165, v24, 8, 0
	v_cmp_gt_u32_e64 s[10:11], 32, v23
	v_lshl_add_u32 v164, v24, 2, s89
	v_sub_u32_e32 v176, v2, v16
	v_mov_b32_e32 v36, v1
	v_mov_b32_e32 v37, v1
	v_mov_b32_e32 v38, v1
	v_mov_b32_e32 v39, v1
	v_mov_b32_e32 v40, v1
	v_mov_b32_e32 v41, v1
	v_mov_b32_e32 v42, v1
	v_mov_b32_e32 v43, v1
	v_mov_b32_e32 v44, v1
	v_mov_b32_e32 v45, v1
	v_mov_b32_e32 v46, v1
	v_mov_b32_e32 v47, v1
	v_mov_b64_e32 v[64:65], v[48:49]
	v_mov_b64_e32 v[18:19], v[34:35]
	v_mov_b64_e32 v[2:3], v[34:35]
	s_mov_b32 s43, s86
	s_mov_b32 s86, 64
	s_waitcnt vmcnt(0) lgkmcnt(0)
	v_mov_b32_e32 v67, v66
	v_mov_b32_e32 v68, v66
	v_mov_b32_e32 v69, v66
	v_mov_b32_e32 v70, v66
	v_mov_b32_e32 v71, v66
	v_mov_b32_e32 v72, v66
	v_mov_b32_e32 v73, v66
	v_mov_b32_e32 v74, v66
	v_mov_b32_e32 v75, v66
	v_add_u32_e32 v175, s12, v0
	s_mov_b32 s82, 0
	v_mov_b32_e32 v177, 0
	v_mov_b32_e32 v178, 0xf149f2ca
	s_mov_b64 s[78:79], 0
	v_mov_b32_e32 v76, v66
	v_mov_b32_e32 v77, v66
	v_mov_b32_e32 v78, v66
	v_mov_b32_e32 v79, v66
	v_mov_b32_e32 v80, v66
	v_mov_b32_e32 v81, v66
	v_mov_b64_e32 v[62:63], v[46:47]
	v_mov_b64_e32 v[60:61], v[44:45]
	v_mov_b64_e32 v[58:59], v[42:43]
	v_mov_b64_e32 v[56:57], v[40:41]
	v_mov_b64_e32 v[54:55], v[38:39]
	v_mov_b64_e32 v[52:53], v[36:37]
	v_mov_b64_e32 v[50:51], v[34:35]
	v_mov_b64_e32 v[20:21], v[36:37]
	v_mov_b64_e32 v[22:23], v[38:39]
	v_mov_b64_e32 v[24:25], v[40:41]
	v_mov_b64_e32 v[26:27], v[42:43]
	v_mov_b64_e32 v[28:29], v[44:45]
	v_mov_b64_e32 v[30:31], v[46:47]
	v_mov_b64_e32 v[32:33], v[48:49]
	v_mov_b64_e32 v[4:5], v[36:37]
	v_mov_b64_e32 v[6:7], v[38:39]
	v_mov_b64_e32 v[8:9], v[40:41]
	v_mov_b64_e32 v[10:11], v[42:43]
	v_mov_b64_e32 v[12:13], v[44:45]
	v_mov_b64_e32 v[14:15], v[46:47]
	v_mov_b64_e32 v[16:17], v[48:49]
	s_and_b32 s0, s82, 1
	s_add_i32 s82, s82, 1
	s_cmp_ge_u32 s82, s7
	s_cbranch_scc1 .LBB0_868

; #define LAS __attribute__((address_space(3)))
; #define GAS __attribute__((address_space(1)))
; __device__ __forceinline__ int opaque_tid() { int t = threadIdx.x; asm volatile("" : "+v"(t)); return t; }
; template <int DK, int MODE> ...
;     const int tid = opaque_tid(), wid = __builtin_amdgcn_readfirstlane(tid >> 6), lane = tid & 63, r32 = lane & 31, hi = lane >> 5;
;     constexpr int PITCH = DK * 2, CPR = DK / 8, NKC = (64 * CPR) / 512, SHM_K = 64 * PITCH, ND = DK / 16;
;     LAS char* V_lds = lds; LAS char* K_lds = lds + OFF_K; LAS float* fk_l = (LAS float*)(lds + OFF_FK); LAS float* ws = (LAS float*)(lds + OFF_WS) + wid * 64;
;     bf16x8 qr[ND];
; #pragma unroll
;     for (int d0 = 0; d0 < ND; ++d0) qr[d0] = *(const GAS bf16x8*)(Qw + (size_t)r32 * qpitch + d0 * 16 + hi * 8);
;     constexpr int NKI = (64 * PITCH) / 8192;
;     const GAS bf16_t* kp[NKI]; int kstep[NKI];
; #pragma unroll
;     for (int i = 0; i < NKI; ++i) { const int off = (wid * NKI + i) * 1024 + lane * 16, row = off / PITCH, rem = off % PITCH, p = rem >> 4, ch = (p & ~7) | ((p & 7) ^ (row & 7));
;         if (DK <= 128 || ch < 16) { kp[i] = (const GAS bf16_t*)Kb + (size_t)row * kpitch + ch * 8; kstep[i] = 64 * kpitch; }
;         else { kp[i] = (const GAS bf16_t*)Kb2 + (size_t)row * k2pitch + (ch - 16) * 8; kstep[i] = 64 * k2pitch; } }
;     const GAS bf16_t* vp[2];
; #pragma unroll
;     for (int i = 0; i < 2; ++i) { const int off = (wid * 2 + i) * 1024 + lane * 16, sub = off >> 9, rem = off & 511, kk = (sub >> 2) * 8 + (rem >> 6), kq = (kk & ~0xC) | ((kk & 4) << 1) | ((kk & 8) >> 1), c = (sub & 3) * 32 + ((rem & 63) >> 1);
;         vp[i] = (const GAS bf16_t*)Vb + (size_t)kq * vpitch + c; }
;     const int vstep = 64 * vpitch;
;     ...
;     float m_reg = -1e30f, l_reg = 0.f;
; #pragma unroll
;     for (int d = 0; d < 4; ++d) o[d] = f32x16{};
;     const int vb00 = (int)(uintptr_t)V_lds + v_rd_base(lane);
;     A_LOAD(0, 0); asm volatile("s_waitcnt vmcnt(0) lgkmcnt(0)\n\ts_barrier" ::: "memory");
; __device__ __forceinline__ void ph_attn(const Args& a, char* lds, int l, int rep) {
;     ...
;         {
;             unsigned o1p[4][8];
;             att::attn_pass<64, 0>((LAS char*)lds, P + qrow * NIN + PC_DQ + h * 128, NIN, P + brow * NIN + PC_DK + h * 128, NIN, nullptr, 0, P + brow * NIN + PC_DV + h * 128, NIN,
;                                   nullptr, 0.f, NT, qlo, 0.125f * LOG2E, o);
.LBB0_1010:
	s_and_b64 vcc, exec, s[0:1]
	s_cbranch_vccz .LBB0_860
	s_cmp_lg_u32 s84, 1
	s_mov_b64 s[0:1], -1
	s_cbranch_scc0 .LBB0_1171
	s_mul_i32 s0, s77, 0x2600
	s_mul_hi_u32 s1, s76, 0x2600
	s_add_i32 s1, s1, s0
	s_mul_i32 s0, s76, 0x2600
	v_readlane_b32 s5, v255, 36
	s_add_u32 s0, s5, s0
	v_readlane_b32 s10, v255, 37
	s_addc_u32 s1, s10, s1
	s_lshl_b32 s2, s86, 7
	v_writelane_b32 v255, s2, 55
	s_lshl_b32 s2, s86, 8
	s_add_u32 s0, s0, s2
	s_addc_u32 s1, s1, 0
	s_add_u32 s88, s0, 0x1a00
	s_addc_u32 s89, s1, 0
	s_add_u32 s0, s5, s16
	s_addc_u32 s1, s10, 0
	s_add_u32 s2, s0, s2
	s_addc_u32 s12, s1, 0
	v_mov_b32_e32 v14, v240
	s_add_u32 s0, s2, 0x1e00
	s_addc_u32 s1, s12, 0
	v_and_b32_e32 v16, 31, v14
	v_mul_u32_u24_e32 v0, 0x1300, v16
	s_add_u32 s78, s2, 0x2200
	v_readfirstlane_b32 s5, v14
	v_bfe_u32 v17, v14, 5, 1
	v_lshlrev_b32_e32 v0, 1, v0
	s_addc_u32 s79, s12, 0
	v_and_b32_e32 v15, 63, v14
	s_waitcnt lgkmcnt(0)
	v_lshl_add_u64 v[2:3], s[88:89], 0, v[0:1]
	v_lshlrev_b32_e32 v0, 4, v17
	s_ashr_i32 s10, s5, 6
	v_lshl_add_u64 v[2:3], v[2:3], 0, v[0:1]
	s_lshl_b32 s13, s10, 10
	v_lshlrev_b32_e32 v18, 4, v15
	global_load_dwordx4 v[98:101], v[2:3], off
	global_load_dwordx4 v[102:105], v[2:3], off offset:32
	global_load_dwordx4 v[106:109], v[2:3], off offset:64
	global_load_dwordx4 v[110:113], v[2:3], off offset:96
	v_or_b32_e32 v2, s13, v18
	v_ashrrev_i32_e32 v3, 31, v2
	v_lshrrev_b32_e32 v3, 25, v3
	v_add_u32_e32 v3, v2, v3
	v_ashrrev_i32_e32 v19, 7, v3
	v_and_b32_e32 v3, 0xffffff80, v3
	v_sub_u32_e32 v2, v2, v3
	s_lshl_b32 s14, s10, 11
	v_ashrrev_i32_e32 v2, 4, v2
	s_ashr_i32 s10, s14, 8
	v_lshrrev_b32_e32 v5, 1, v14
	v_lshrrev_b32_e32 v239, 1, v19
	v_bitop3_b32 v2, v239, v2, 7 bitop3:0x6c
	v_bfe_u32 v4, v14, 2, 2
	s_and_b32 s11, s10, 0xfffff0
	v_and_b32_e32 v5, 8, v5
	v_lshlrev_b32_e32 v2, 3, v2
	s_lshr_b32 s10, s10, 1
	v_or3_b32 v4, v5, v4, s11
	s_movk_i32 s15, 0x2600
	v_ashrrev_i32_e32 v3, 31, v2
	v_lshlrev_b32_e32 v20, 3, v15
	v_and_or_b32 v4, s10, 4, v4
	v_and_b32_e32 v5, 32, v14
	v_mov_b64_e32 v[12:13], s[0:1]
	v_and_or_b32 v8, v20, 24, v5
	v_mul_hi_i32_i24_e32 v5, 0x2600, v4
	v_mul_i32_i24_e32 v4, 0x2600, v4
	v_mad_i64_i32 v[12:13], s[10:11], v19, s15, v[12:13]
	v_lshlrev_b64 v[2:3], 1, v[2:3]
	s_add_i32 s82, s13, 0
	v_lshl_add_u64 v[6:7], s[78:79], 0, v[4:5]
	v_lshlrev_b32_e32 v8, 1, v8
	v_mov_b32_e32 v9, v1
	v_lshl_add_u64 v[12:13], v[12:13], 0, v[2:3]
	s_add_i32 m0, s82, 0x8000
	s_add_i32 s83, s14, 0
	v_lshl_add_u64 v[6:7], v[6:7], 0, v[8:9]
	global_load_lds_dwordx4 v[12:13], off
	s_mov_b32 m0, s83
	v_lshl_add_u64 v[10:11], v[6:7], 0, s[96:97]
	global_load_lds_dwordx4 v[6:7], off
	s_add_i32 m0, s83, 0x400
	s_and_b32 s5, s5, 0x3fffffc0
	global_load_lds_dwordx4 v[10:11], off
	s_lshl_b32 s5, s5, 2
	s_add_i32 s5, s5, 0
	v_lshlrev_b32_e32 v9, 4, v14
	s_movk_i32 s13, 0x70
	v_writelane_b32 v255, s86, 56
	v_lshlrev_b32_e32 v6, 1, v14
	s_add_i32 s5, s5, 0x14200
	s_or_b32 s86, s6, 31
	v_lshlrev_b32_e32 v239, 3, v14
	v_and_b32_e32 v10, 0x70, v239
	s_waitcnt vmcnt(0)
	v_bitop3_b32 v120, v0, v239, s13 bitop3:0x78
	s_movk_i32 s13, 0x60
	v_and_b32_e32 v6, 32, v6
	v_bitop3_b32 v123, v0, v10, s13 bitop3:0x36
	s_movk_i32 s13, 0x118
	s_add_u32 s84, s2, 0x9a280
	v_writelane_b32 v255, s16, 57
	v_and_or_b32 v6, v20, s13, v6
	s_addc_u32 s85, s12, 0
	v_mad_i64_i32 v[2:3], s[12:13], v19, s15, v[2:3]
	v_readlane_b32 s2, v255, 52
	v_readlane_b32 s12, v255, 53
	v_lshl_add_u64 v[2:3], s[0:1], 0, v[2:3]
	s_add_i32 s2, s2, s12
	v_and_b32_e32 v7, 0xc0, v18
	s_waitcnt vmcnt(0) lgkmcnt(0)
	s_barrier
	v_lshl_add_u32 v119, v16, 7, 0
	v_lshl_add_u32 v118, v16, 2, s5
	v_lshlrev_b32_e32 v9, 2, v17
	v_or_b32_e32 v4, v4, v8
	v_lshl_add_u64 v[116:117], v[2:3], 0, s[68:69]
	v_add_u32_e32 v2, s2, v16
	v_mov_b32_e32 v16, v1
	v_mov_b32_e32 v17, v1
	v_cmp_gt_u32_e64 s[10:11], 32, v15
	v_bitop3_b32 v121, v0, v10, 32 bitop3:0x36
	v_bitop3_b32 v122, v0, v10, 64 bitop3:0x36
	v_add3_u32 v124, v7, 0, v6
	v_lshl_add_u64 v[114:115], s[84:85], 0, v[4:5]
	v_sub_u32_e32 v125, v2, v9
	v_mov_b32_e32 v2, v1
	v_mov_b32_e32 v3, v1
	v_mov_b32_e32 v4, v1
	v_mov_b32_e32 v5, v1
	v_mov_b32_e32 v6, v1
	v_mov_b32_e32 v7, v1
	v_mov_b32_e32 v8, v1
	v_mov_b32_e32 v9, v1
	v_mov_b32_e32 v10, v1
	v_mov_b32_e32 v11, v1
	v_mov_b32_e32 v12, v1
	v_mov_b32_e32 v13, v1
	v_mov_b32_e32 v14, v1
	v_mov_b32_e32 v15, v1
	v_mov_b64_e32 v[32:33], v[16:17]
	v_mov_b64_e32 v[48:49], v[16:17]
	v_mov_b64_e32 v[64:65], v[16:17]
	s_mov_b32 s43, 63
	s_mov_b32 s93, 1
	s_sub_i32 s4, 0xffffffe0, s4
	v_writelane_b32 v255, s2, 58
	v_mov_b32_e32 v126, 0
	v_mov_b32_e32 v128, 0xf149f2ca
	v_mov_b64_e32 v[30:31], v[14:15]
	v_mov_b64_e32 v[28:29], v[12:13]
	v_mov_b64_e32 v[26:27], v[10:11]
	v_mov_b64_e32 v[24:25], v[8:9]
	v_mov_b64_e32 v[22:23], v[6:7]
	v_mov_b64_e32 v[20:21], v[4:5]
	v_mov_b64_e32 v[18:19], v[2:3]
	v_mov_b64_e32 v[46:47], v[14:15]
	v_mov_b64_e32 v[44:45], v[12:13]
	v_mov_b64_e32 v[42:43], v[10:11]
	v_mov_b64_e32 v[40:41], v[8:9]
	v_mov_b64_e32 v[38:39], v[6:7]
	v_mov_b64_e32 v[36:37], v[4:5]
	v_mov_b64_e32 v[34:35], v[2:3]
	v_mov_b64_e32 v[62:63], v[14:15]
	v_mov_b64_e32 v[60:61], v[12:13]
	v_mov_b64_e32 v[58:59], v[10:11]
	v_mov_b64_e32 v[56:57], v[8:9]
	v_mov_b64_e32 v[54:55], v[6:7]
	v_mov_b64_e32 v[52:53], v[4:5]
	v_mov_b64_e32 v[50:51], v[2:3]
	s_add_i32 s2, s93, -1
	s_and_b32 s2, s2, 1
	s_cmp_ge_u32 s93, s7
	s_cbranch_scc1 .LBB0_1014

; #define GAS __attribute__((address_space(1)))
; __device__ __forceinline__ int crow(int r, int hi) { return (r & 3) + 8 * (r >> 2) + 4 * hi; }
; __device__ __forceinline__ int v_rd_base(int lane) { return ((lane & 3) << 3) | (((lane >> 2) & 3) << 6) | (((lane >> 4) & 1) << 5) | (((lane >> 5) & 1) << 8); }
; template <int DK, int MODE> ...
;     ...
;     bf16x8 qr[ND];
; #pragma unroll
;     for (int d0 = 0; d0 < ND; ++d0) qr[d0] = *(const GAS bf16x8*)(Qw + (size_t)r32 * qpitch + d0 * 16 + hi * 8);
;     constexpr int NKI = (64 * PITCH) / 8192;
;     const GAS bf16_t* kp[NKI]; int kstep[NKI];
; #pragma unroll
;     for (int i = 0; i < NKI; ++i) { const int off = (wid * NKI + i) * 1024 + lane * 16, row = off / PITCH, rem = off % PITCH, p = rem >> 4, ch = (p & ~7) | ((p & 7) ^ (row & 7));
;         if (DK <= 128 || ch < 16) { kp[i] = (const GAS bf16_t*)Kb + (size_t)row * kpitch + ch * 8; kstep[i] = 64 * kpitch; }
;         else { kp[i] = (const GAS bf16_t*)Kb2 + (size_t)row * k2pitch + (ch - 16) * 8; kstep[i] = 64 * k2pitch; } }
;     const GAS bf16_t* vp[2];
; #pragma unroll
;     for (int i = 0; i < 2; ++i) { const int off = (wid * 2 + i) * 1024 + lane * 16, sub = off >> 9, rem = off & 511, kk = (sub >> 2) * 8 + (rem >> 6), kq = (kk & ~0xC) | ((kk & 4) << 1) | ((kk & 8) >> 1), c = (sub & 3) * 32 + ((rem & 63) >> 1);
;         vp[i] = (const GAS bf16_t*)Vb + (size_t)kq * vpitch + c; }
;     const int vstep = 64 * vpitch;
;     ...
;     float m_reg = -1e30f, l_reg = 0.f;
; #pragma unroll
;     for (int d = 0; d < 4; ++d) o[d] = f32x16{};
;     const int vb00 = (int)(uintptr_t)V_lds + v_rd_base(lane);
;     A_LOAD(0, 0); asm volatile("s_waitcnt vmcnt(0) lgkmcnt(0)\n\ts_barrier" ::: "memory");
;     ...
;     if (hi == 0) ws[32 + r32] = l_reg; asm volatile("s_waitcnt lgkmcnt(0)" ::: "memory");
; #pragma unroll
;     for (int r = 0; r < 16; ++r) { const float rl = __builtin_amdgcn_rcpf(ws[32 + crow(r, hi)]);
; #pragma unroll
;         for (int d = 0; d < 4; ++d) o[d][r] *= rl; }
.LBB0_1025:
	s_and_saveexec_b64 s[12:13], s[10:11]
	ds_write_b32 v118, v126 offset:128
	s_or_b64 exec, exec, s[12:13]
	s_waitcnt lgkmcnt(0)
	v_add_u32_e32 v0, s5, v0
	ds_read_b128 v[66:69], v0 offset:128
	ds_read_b128 v[70:73], v0 offset:160
	s_add_u32 s0, s0, 0x80
	s_addc_u32 s1, s1, 0
	s_movk_i32 s83, 0x2600
	s_waitcnt lgkmcnt(0)
	v_rcp_f32_e32 v66, v66
	v_rcp_f32_e32 v67, v67
	s_mov_b32 s43, 63
	s_mov_b32 s82, 1
	v_mul_f32_e32 v74, v2, v66
	v_rcp_f32_e32 v2, v68
	v_mul_f32_e32 v18, v18, v66
	v_mul_f32_e32 v34, v34, v66
	v_mul_f32_e32 v50, v50, v66
	v_mul_f32_e32 v66, v3, v67
	v_mul_f32_e32 v19, v19, v67
	v_mul_f32_e32 v35, v35, v67
	v_mul_f32_e32 v51, v51, v67
	v_mul_f32_e32 v67, v4, v2
	v_rcp_f32_e32 v3, v69
	v_mul_f32_e32 v20, v20, v2
	v_mul_f32_e32 v36, v36, v2
	v_mul_f32_e32 v52, v52, v2
	v_rcp_f32_e32 v2, v70
	v_mul_f32_e32 v68, v5, v3
	v_mul_f32_e32 v21, v21, v3
	v_mul_f32_e32 v37, v37, v3
	v_mul_f32_e32 v53, v53, v3
	v_mul_f32_e32 v69, v6, v2
	v_rcp_f32_e32 v3, v71
	v_rcp_f32_e32 v6, v72
	v_rcp_f32_e32 v72, v73
	v_mul_f32_e32 v22, v22, v2
	v_mul_f32_e32 v38, v38, v2
	v_mul_f32_e32 v54, v54, v2
	v_mul_f32_e32 v70, v7, v3
	v_mul_f32_e32 v23, v23, v3
	v_mul_f32_e32 v39, v39, v3
	v_mul_f32_e32 v55, v55, v3
	v_mul_f32_e32 v71, v8, v6
	v_mul_f32_e32 v24, v24, v6
	ds_read_b128 v[2:5], v0 offset:192
	v_mul_f32_e32 v40, v40, v6
	v_mul_f32_e32 v56, v56, v6
	v_mul_f32_e32 v73, v9, v72
	ds_read_b128 v[6:9], v0 offset:224
	s_waitcnt lgkmcnt(0)
	v_rcp_f32_e32 v0, v2
	v_rcp_f32_e32 v3, v3
	v_rcp_f32_e32 v4, v4
	v_rcp_f32_e32 v5, v5
	v_rcp_f32_e32 v6, v6
	v_rcp_f32_e32 v7, v7
	v_rcp_f32_e32 v8, v8
	v_rcp_f32_e32 v9, v9
	v_mul_f32_e32 v14, v14, v6
	v_mul_f32_e32 v10, v10, v0
	v_mul_f32_e32 v11, v11, v3
	v_mul_f32_e32 v12, v12, v4
	v_mul_f32_e32 v13, v13, v5
	v_mul_f32_e32 v15, v15, v7
	v_mul_f32_e32 v16, v16, v8
	s_waitcnt lgkmcnt(0)
	v_cvt_pk_bf16_f32 v152, v74, v66
	v_cvt_pk_bf16_f32 v142, v67, v68
	v_cvt_pk_bf16_f32 v138, v69, v70
	v_cvt_pk_bf16_f32 v134, v71, v73
	v_cvt_pk_bf16_f32 v130, v10, v11
	v_cvt_pk_bf16_f32 v126, v12, v13
	v_cvt_pk_bf16_f32 v122, v14, v15
	v_mov_b32_e32 v14, v240
	v_mul_f32_e32 v2, v25, v72
	v_mul_f32_e32 v25, v41, v72
	v_mul_f32_e32 v41, v57, v72
	v_mul_f32_e32 v26, v26, v0
	v_mul_f32_e32 v42, v42, v0
	v_mul_f32_e32 v0, v58, v0
	v_mul_f32_e32 v27, v27, v3
	v_mul_f32_e32 v43, v43, v3
	v_mul_f32_e32 v3, v59, v3
	v_mul_f32_e32 v28, v28, v4
	v_mul_f32_e32 v44, v44, v4
	v_mul_f32_e32 v4, v60, v4
	v_mul_f32_e32 v29, v29, v5
	v_mul_f32_e32 v45, v45, v5
	v_mul_f32_e32 v5, v61, v5
	v_mul_f32_e32 v30, v30, v6
	v_mul_f32_e32 v46, v46, v6
	v_mul_f32_e32 v6, v62, v6
	v_mul_f32_e32 v31, v31, v7
	v_mul_f32_e32 v47, v47, v7
	v_mul_f32_e32 v7, v63, v7
	v_mul_f32_e32 v32, v32, v8
	v_mul_f32_e32 v48, v48, v8
	v_mul_f32_e32 v8, v64, v8
	v_mul_f32_e32 v17, v17, v9
	v_mul_f32_e32 v33, v33, v9
	v_mul_f32_e32 v49, v49, v9
	v_mul_f32_e32 v9, v65, v9
	v_cvt_pk_bf16_f32 v118, v16, v17
	v_cvt_pk_bf16_f32 v153, v18, v19
	v_cvt_pk_bf16_f32 v143, v20, v21
	v_cvt_pk_bf16_f32 v139, v22, v23
	v_cvt_pk_bf16_f32 v135, v24, v2
	v_cvt_pk_bf16_f32 v131, v26, v27
	v_cvt_pk_bf16_f32 v127, v28, v29
	v_cvt_pk_bf16_f32 v123, v30, v31
	v_cvt_pk_bf16_f32 v119, v32, v33
	v_cvt_pk_bf16_f32 v154, v34, v35
	v_cvt_pk_bf16_f32 v144, v36, v37
	v_cvt_pk_bf16_f32 v140, v38, v39
	v_cvt_pk_bf16_f32 v136, v40, v25
	v_cvt_pk_bf16_f32 v132, v42, v43
	v_cvt_pk_bf16_f32 v128, v44, v45
	v_cvt_pk_bf16_f32 v124, v46, v47
	v_cvt_pk_bf16_f32 v120, v48, v49
	v_cvt_pk_bf16_f32 v155, v50, v51
	v_cvt_pk_bf16_f32 v145, v52, v53
	v_cvt_pk_bf16_f32 v141, v54, v55
	v_cvt_pk_bf16_f32 v137, v56, v41
	v_cvt_pk_bf16_f32 v133, v0, v3
	v_cvt_pk_bf16_f32 v129, v4, v5
	v_cvt_pk_bf16_f32 v125, v6, v7
	v_cvt_pk_bf16_f32 v121, v8, v9
	v_mov_b64_e32 v[12:13], s[0:1]
	v_and_b32_e32 v16, 31, v14
	v_mul_u32_u24_e32 v0, 0x1300, v16
	v_readfirstlane_b32 s2, v14
	v_bfe_u32 v17, v14, 5, 1
	v_lshlrev_b32_e32 v0, 1, v0
	v_and_b32_e32 v15, 63, v14
	v_lshl_add_u64 v[2:3], s[88:89], 0, v[0:1]
	v_lshlrev_b32_e32 v0, 4, v17
	s_ashr_i32 s5, s2, 6
	v_lshl_add_u64 v[2:3], v[2:3], 0, v[0:1]
	s_lshl_b32 s12, s5, 10
	v_lshlrev_b32_e32 v18, 4, v15
	global_load_dwordx4 v[98:101], v[2:3], off offset:128
	global_load_dwordx4 v[102:105], v[2:3], off offset:160
	global_load_dwordx4 v[106:109], v[2:3], off offset:192
	global_load_dwordx4 v[110:113], v[2:3], off offset:224
	v_or_b32_e32 v2, s12, v18
	v_ashrrev_i32_e32 v3, 31, v2
	v_lshrrev_b32_e32 v3, 25, v3
	v_add_u32_e32 v3, v2, v3
	v_ashrrev_i32_e32 v19, 7, v3
	v_and_b32_e32 v3, 0xffffff80, v3
	s_lshl_b32 s5, s5, 11
	v_sub_u32_e32 v2, v2, v3
	s_ashr_i32 s10, s5, 8
	v_lshrrev_b32_e32 v5, 1, v14
	v_ashrrev_i32_e32 v2, 4, v2
	v_bfe_u32 v4, v14, 2, 2
	s_and_b32 s11, s10, 0xfffff0
	v_and_b32_e32 v5, 8, v5
	v_lshrrev_b32_e32 v239, 1, v19
	v_bitop3_b32 v2, v239, v2, 7 bitop3:0x6c
	s_lshr_b32 s10, s10, 1
	v_or3_b32 v4, v5, v4, s11
	v_lshlrev_b32_e32 v2, 3, v2
	v_lshlrev_b32_e32 v20, 3, v15
	v_and_or_b32 v4, s10, 4, v4
	v_and_b32_e32 v5, 32, v14
	v_ashrrev_i32_e32 v3, 31, v2
	v_and_or_b32 v8, v20, 24, v5
	v_mul_hi_i32_i24_e32 v5, 0x2600, v4
	v_mul_i32_i24_e32 v4, 0x2600, v4
	v_lshl_add_u64 v[6:7], s[78:79], 0, v[4:5]
	v_mad_i64_i32 v[12:13], s[10:11], v19, s83, v[12:13]
	v_lshlrev_b64 v[2:3], 1, v[2:3]
	s_add_i32 s78, s12, 0
	v_lshlrev_b32_e32 v8, 1, v8
	v_mov_b32_e32 v9, v1
	v_lshl_add_u64 v[12:13], v[12:13], 0, v[2:3]
	s_add_i32 m0, s78, 0x8000
	s_add_i32 s5, s5, 0
	v_lshl_add_u64 v[6:7], v[6:7], 0, v[8:9]
	global_load_lds_dwordx4 v[12:13], off
	s_mov_b32 m0, s5
	v_lshl_add_u64 v[10:11], v[6:7], 0, s[96:97]
	global_load_lds_dwordx4 v[6:7], off
	s_add_i32 m0, s5, 0x400
	s_and_b32 s2, s2, 0x3fffffc0
	global_load_lds_dwordx4 v[10:11], off
	s_lshl_b32 s2, s2, 2
	s_add_i32 s79, s2, 0
	v_lshlrev_b32_e32 v9, 4, v14
	s_movk_i32 s2, 0x70
	v_lshlrev_b32_e32 v6, 1, v14
	v_lshlrev_b32_e32 v239, 3, v14
	v_and_b32_e32 v10, 0x70, v239
	v_bitop3_b32 v158, v0, v239, s2 bitop3:0x78
	s_movk_i32 s2, 0x60
	v_mad_i64_i32 v[2:3], s[12:13], v19, s83, v[2:3]
	s_add_i32 s79, s79, 0x14200
	v_and_b32_e32 v6, 32, v6
	v_bitop3_b32 v161, v0, v10, s2 bitop3:0x36
	s_movk_i32 s2, 0x118
	v_lshl_add_u64 v[2:3], s[0:1], 0, v[2:3]
	v_readlane_b32 s0, v255, 58
	v_and_b32_e32 v7, 0xc0, v18
	s_waitcnt vmcnt(0) lgkmcnt(0)
	s_barrier
; __device__ __forceinline__ int v_rd_base(int lane) { return ((lane & 3) << 3) | (((lane >> 2) & 3) << 6) | (((lane >> 4) & 1) << 5) | (((lane >> 5) & 1) << 8); }
; template <int DK, int MODE> ...
;     ...
;     float m_reg = -1e30f, l_reg = 0.f;
; #pragma unroll
;     for (int d = 0; d < 4; ++d) o[d] = f32x16{};
;     const int vb00 = (int)(uintptr_t)V_lds + v_rd_base(lane);
;     A_LOAD(0, 0); asm volatile("s_waitcnt vmcnt(0) lgkmcnt(0)\n\ts_barrier" ::: "memory");
;     for (int t = 0; t < NT; ++t) {
;         const int buf = t & 1, kb = t * 64;
;         if (t + 1 < NT) A_LOAD(t + 1, buf ^ 1);
	v_lshl_add_u32 v157, v16, 7, 0
	v_lshl_add_u32 v156, v16, 2, s79
	v_and_or_b32 v6, v20, s2, v6
	v_lshlrev_b32_e32 v9, 2, v17
	v_or_b32_e32 v4, v4, v8
	v_lshl_add_u64 v[116:117], v[2:3], 0, s[68:69]
	v_add_u32_e32 v2, s0, v16
	v_mov_b32_e32 v16, v1
	v_mov_b32_e32 v17, v1
	v_cmp_gt_u32_e64 s[10:11], 32, v15
	v_bitop3_b32 v159, v0, v10, 32 bitop3:0x36
	v_bitop3_b32 v160, v0, v10, 64 bitop3:0x36
	v_add3_u32 v162, v7, 0, v6
	v_lshl_add_u64 v[114:115], s[84:85], 0, v[4:5]
	v_sub_u32_e32 v163, v2, v9
	v_mov_b32_e32 v2, v1
	v_mov_b32_e32 v3, v1
	v_mov_b32_e32 v4, v1
	v_mov_b32_e32 v5, v1
	v_mov_b32_e32 v6, v1
	v_mov_b32_e32 v7, v1
	v_mov_b32_e32 v8, v1
	v_mov_b32_e32 v9, v1
	v_mov_b32_e32 v10, v1
	v_mov_b32_e32 v11, v1
	v_mov_b32_e32 v12, v1
	v_mov_b32_e32 v13, v1
	v_mov_b32_e32 v14, v1
	v_mov_b32_e32 v15, v1
	v_mov_b64_e32 v[32:33], v[16:17]
	v_mov_b64_e32 v[48:49], v[16:17]
	v_mov_b64_e32 v[64:65], v[16:17]
	v_mov_b32_e32 v164, 0
	v_mov_b32_e32 v166, 0xf149f2ca
	v_mov_b64_e32 v[30:31], v[14:15]
	v_mov_b64_e32 v[28:29], v[12:13]
	v_mov_b64_e32 v[26:27], v[10:11]
	v_mov_b64_e32 v[24:25], v[8:9]
	v_mov_b64_e32 v[22:23], v[6:7]
	v_mov_b64_e32 v[20:21], v[4:5]
	v_mov_b64_e32 v[18:19], v[2:3]
	v_mov_b64_e32 v[46:47], v[14:15]
	v_mov_b64_e32 v[44:45], v[12:13]
	v_mov_b64_e32 v[42:43], v[10:11]
	v_mov_b64_e32 v[40:41], v[8:9]
	v_mov_b64_e32 v[38:39], v[6:7]
	v_mov_b64_e32 v[36:37], v[4:5]
	v_mov_b64_e32 v[34:35], v[2:3]
	v_mov_b64_e32 v[62:63], v[14:15]
	v_mov_b64_e32 v[60:61], v[12:13]
	v_mov_b64_e32 v[58:59], v[10:11]
	v_mov_b64_e32 v[56:57], v[8:9]
	v_mov_b64_e32 v[54:55], v[6:7]
	v_mov_b64_e32 v[52:53], v[4:5]
	v_mov_b64_e32 v[50:51], v[2:3]
	v_readlane_b32 s85, v255, 28
	s_add_i32 s0, s82, -1
	s_and_b32 s2, s0, 1
	s_cmp_ge_u32 s82, s7
	s_cbranch_scc1 .LBB0_1029

; #define LAS __attribute__((address_space(3)))
; #define GAS __attribute__((address_space(1)))
; __device__ __forceinline__ int opaque_tid() { int t = threadIdx.x; asm volatile("" : "+v"(t)); return t; }
; template <int DK, int MODE> ...
;     const int tid = opaque_tid(), wid = __builtin_amdgcn_readfirstlane(tid >> 6), lane = tid & 63, r32 = lane & 31, hi = lane >> 5;
;     constexpr int PITCH = DK * 2, CPR = DK / 8, NKC = (64 * CPR) / 512, SHM_K = 64 * PITCH, ND = DK / 16;
;     LAS char* V_lds = lds; LAS char* K_lds = lds + OFF_K; LAS float* fk_l = (LAS float*)(lds + OFF_FK); LAS float* ws = (LAS float*)(lds + OFF_WS) + wid * 64;
;     bf16x8 qr[ND];
; #pragma unroll
;     for (int d0 = 0; d0 < ND; ++d0) qr[d0] = *(const GAS bf16x8*)(Qw + (size_t)r32 * qpitch + d0 * 16 + hi * 8);
;     constexpr int NKI = (64 * PITCH) / 8192;
;     const GAS bf16_t* kp[NKI]; int kstep[NKI];
; #pragma unroll
;     for (int i = 0; i < NKI; ++i) { const int off = (wid * NKI + i) * 1024 + lane * 16, row = off / PITCH, rem = off % PITCH, p = rem >> 4, ch = (p & ~7) | ((p & 7) ^ (row & 7));
;         if (DK <= 128 || ch < 16) { kp[i] = (const GAS bf16_t*)Kb + (size_t)row * kpitch + ch * 8; kstep[i] = 64 * kpitch; }
;         else { kp[i] = (const GAS bf16_t*)Kb2 + (size_t)row * k2pitch + (ch - 16) * 8; kstep[i] = 64 * k2pitch; } }
; __device__ __forceinline__ void ph_attn(const Args& a, char* lds, int l, int rep) {
;     ...
;         if (type == 1) {
;             const bf16_t* QM = WSP(bf16_t, WS_QM); const bf16_t* KVM = WSP(bf16_t, WS_KVM);
;             att::attn_pass<192, 0>((LAS char*)lds, QM + qrow * 768 + h * 192, 768, KVM + brow * 1024 + h * 256, 1024, P + brow * NIN + PC_KR, NIN, KVM + brow * 1024 + h * 256 + 128, 1024,
;                                    nullptr, 0.f, NT, qlo, 0.07216878364870322f * LOG2E, o);
;             att::store_o(o, MIX + qrow * DM + 512 + h * 128, DM, r32, hi);
.LBB0_1171:
	s_and_b64 vcc, exec, s[0:1]
	s_cbranch_vccz .LBB0_860
	s_mul_i32 s0, s77, 0x600
	s_mul_hi_u32 s1, s76, 0x600
	s_add_i32 s1, s1, s0
	s_mul_i32 s0, s76, 0x600
	v_readlane_b32 s2, v255, 45
	s_add_u32 s0, s2, s0
	v_readlane_b32 s2, v255, 46
	v_mov_b32_e32 v16, v240
	s_addc_u32 s1, s2, s1
	s_mul_i32 s2, s86, 0x180
	s_add_u32 s0, s0, s2
	v_and_b32_e32 v14, 31, v16
	v_mul_u32_u24_e32 v0, 0x300, v14
	s_addc_u32 s1, s1, 0
	v_bfe_u32 v15, v16, 5, 1
	v_lshlrev_b32_e32 v0, 1, v0
	s_waitcnt lgkmcnt(0)
	v_lshl_add_u64 v[2:3], s[0:1], 0, v[0:1]
	v_lshlrev_b32_e32 v152, 4, v15
	v_mov_b32_e32 v153, v1
	v_lshl_add_u64 v[2:3], v[2:3], 0, v[152:153]
	global_load_dwordx4 v[98:101], v[2:3], off
	global_load_dwordx4 v[102:105], v[2:3], off offset:32
	global_load_dwordx4 v[106:109], v[2:3], off offset:64
	global_load_dwordx4 v[110:113], v[2:3], off offset:96
	global_load_dwordx4 v[114:117], v[2:3], off offset:128
	global_load_dwordx4 v[118:121], v[2:3], off offset:160
	global_load_dwordx4 v[122:125], v[2:3], off offset:192
	global_load_dwordx4 v[126:129], v[2:3], off offset:224
	global_load_dwordx4 v[130:133], v[2:3], off offset:256
	global_load_dwordx4 v[134:137], v[2:3], off offset:288
	global_load_dwordx4 v[138:141], v[2:3], off offset:320
	global_load_dwordx4 v[142:145], v[2:3], off offset:352
	v_readlane_b32 s0, v255, 54
	s_lshl_b32 s0, s0, 11
	v_readlane_b32 s1, v255, 47
	s_add_u32 s0, s1, s0
	v_readlane_b32 s1, v255, 48
	s_addc_u32 s1, s1, 0
	s_lshl_b32 s2, s86, 9
	s_add_u32 s0, s0, s2
	s_addc_u32 s1, s1, 0
	v_readlane_b32 s2, v255, 36
	s_add_u32 s2, s2, s16
	v_readlane_b32 s4, v255, 37
	s_addc_u32 s4, s4, 0
	s_add_u32 s10, s2, 0x1100
	s_addc_u32 s11, s4, 0
	v_readfirstlane_b32 s4, v16
	v_and_b32_e32 v17, 63, v16
	s_ashr_i32 s5, s4, 6
	v_lshlrev_b32_e32 v18, 4, v17
	s_mul_i32 s2, s5, 0xc00
	v_or_b32_e32 v0, s2, v18
	s_mov_b32 s12, 0x2aaaaaab
	v_mul_hi_i32 v2, v0, s12
	v_lshrrev_b32_e32 v3, 31, v2
	v_ashrrev_i32_e32 v2, 6, v2
	v_add_u32_e32 v6, v2, v3
	v_mul_i32_i24_e32 v2, 0x180, v6
	v_sub_u32_e32 v0, v0, v2
	v_ashrrev_i32_e32 v0, 4, v0
	v_lshrrev_b32_e32 v239, 1, v6
	v_bitop3_b32 v0, v239, v0, 7 bitop3:0x6c
	v_cmp_lt_i32_e32 vcc, 15, v0
	v_ashrrev_i32_e32 v7, 31, v6
	v_lshlrev_b32_e32 v4, 3, v0
	s_and_saveexec_b64 s[12:13], vcc
	s_xor_b64 s[12:13], exec, s[12:13]
	v_mul_hi_i32_i24_e32 v3, 0x2600, v6
	v_mul_i32_i24_e32 v2, 0x2600, v6
	v_lshl_add_u64 v[2:3], s[10:11], 0, v[2:3]
	v_mov_b32_e32 v5, v1
	s_movk_i32 s14, 0xff00
	v_lshl_add_u64 v[2:3], v[4:5], 1, v[2:3]
	s_mov_b32 s15, -1
	v_lshl_add_u64 v[2:3], v[2:3], 0, s[14:15]
	s_or_saveexec_b64 s[12:13], s[12:13]
	v_mov_b32_e32 v19, 0x4c000
	s_xor_b64 exec, exec, s[12:13]
	v_lshlrev_b64 v[2:3], 11, v[6:7]
	v_lshl_add_u64 v[2:3], s[0:1], 0, v[2:3]
	v_ashrrev_i32_e32 v5, 31, v4
	v_lshl_add_u64 v[2:3], v[4:5], 1, v[2:3]
	v_mov_b32_e32 v19, 0x10000
	s_or_b64 exec, exec, s[12:13]
	s_add_i32 s12, s2, 0x400
	v_or_b32_e32 v0, s12, v18
	s_mov_b32 s12, 0x2aaaaaab
	v_mul_hi_i32 v4, v0, s12
	v_lshrrev_b32_e32 v5, 31, v4
	v_ashrrev_i32_e32 v4, 6, v4
	v_add_u32_e32 v8, v4, v5
	v_mul_i32_i24_e32 v4, 0x180, v8
	v_sub_u32_e32 v0, v0, v4
	v_ashrrev_i32_e32 v0, 4, v0
	v_lshrrev_b32_e32 v239, 1, v8
	v_bitop3_b32 v0, v239, v0, 7 bitop3:0x6c
	v_cmp_lt_i32_e32 vcc, 15, v0
	v_ashrrev_i32_e32 v9, 31, v8
	v_lshlrev_b32_e32 v0, 3, v0
	s_and_saveexec_b64 s[12:13], vcc
	s_xor_b64 s[12:13], exec, s[12:13]
	v_mul_hi_i32_i24_e32 v5, 0x2600, v8
	v_mul_i32_i24_e32 v4, 0x2600, v8
	v_lshl_add_u64 v[4:5], s[10:11], 0, v[4:5]
	s_movk_i32 s14, 0xff00
	v_lshl_add_u64 v[4:5], v[0:1], 1, v[4:5]
	s_mov_b32 s15, -1
	v_lshl_add_u64 v[4:5], v[4:5], 0, s[14:15]
	s_or_saveexec_b64 s[12:13], s[12:13]
	v_mov_b64_e32 v[6:7], 0x4c000
	s_xor_b64 exec, exec, s[12:13]
	v_lshlrev_b64 v[4:5], 11, v[8:9]
	v_lshl_add_u64 v[4:5], s[0:1], 0, v[4:5]
	v_ashrrev_i32_e32 v7, 31, v0
	v_mov_b32_e32 v6, v0
	v_lshl_add_u64 v[4:5], v[6:7], 1, v[4:5]
	v_mov_b64_e32 v[6:7], 0x10000
	s_or_b64 exec, exec, s[12:13]
	s_add_i32 s12, s2, 0x800
	v_or_b32_e32 v0, s12, v18
	s_mov_b32 s12, 0x2aaaaaab
	v_mul_hi_i32 v7, v0, s12
	v_lshrrev_b32_e32 v8, 31, v7
	v_ashrrev_i32_e32 v7, 6, v7
	v_add_u32_e32 v12, v7, v8
	v_mul_i32_i24_e32 v7, 0x180, v12
	v_sub_u32_e32 v0, v0, v7
	v_ashrrev_i32_e32 v0, 4, v0
	v_lshrrev_b32_e32 v239, 1, v12
	v_bitop3_b32 v0, v239, v0, 7 bitop3:0x6c
	v_cmp_lt_i32_e32 vcc, 15, v0
	v_ashrrev_i32_e32 v13, 31, v12
	v_lshlrev_b32_e32 v0, 3, v0
	s_and_saveexec_b64 s[12:13], vcc
	s_xor_b64 s[12:13], exec, s[12:13]
	v_mul_hi_i32_i24_e32 v9, 0x2600, v12
	v_mul_i32_i24_e32 v8, 0x2600, v12
	v_lshl_add_u64 v[8:9], s[10:11], 0, v[8:9]
	s_movk_i32 s10, 0xff00
	v_lshl_add_u64 v[8:9], v[0:1], 1, v[8:9]
	s_mov_b32 s11, -1
	v_lshl_add_u64 v[8:9], v[8:9], 0, s[10:11]
; #define LAS __attribute__((address_space(3)))
; #define GAS __attribute__((address_space(1)))
; __device__ __forceinline__ int v_rd_base(int lane) { return ((lane & 3) << 3) | (((lane >> 2) & 3) << 6) | (((lane >> 4) & 1) << 5) | (((lane >> 5) & 1) << 8); }
; template <int DK, int MODE> ...
;     ...
;     const GAS bf16_t* vp[2];
; #pragma unroll
;     for (int i = 0; i < 2; ++i) { const int off = (wid * 2 + i) * 1024 + lane * 16, sub = off >> 9, rem = off & 511, kk = (sub >> 2) * 8 + (rem >> 6), kq = (kk & ~0xC) | ((kk & 4) << 1) | ((kk & 8) >> 1), c = (sub & 3) * 32 + ((rem & 63) >> 1);
;         vp[i] = (const GAS bf16_t*)Vb + (size_t)kq * vpitch + c; }
;     const int vstep = 64 * vpitch;
;     ...
;     float m_reg = -1e30f, l_reg = 0.f;
; #pragma unroll
;     for (int d = 0; d < 4; ++d) o[d] = f32x16{};
;     const int vb00 = (int)(uintptr_t)V_lds + v_rd_base(lane);
;     A_LOAD(0, 0); asm volatile("s_waitcnt vmcnt(0) lgkmcnt(0)\n\ts_barrier" ::: "memory");
;     for (int t = 0; t < NT; ++t) {
;         const int buf = t & 1, kb = t * 64;
;         if (t + 1 < NT) A_LOAD(t + 1, buf ^ 1);
;         const bool act = (MODE == 2) || (kb <= qlo + 31);
;         if (act) {
;             f32x16 p0 = f32x16{}, p1 = f32x16{};
;             const LAS char* kbase = K_lds + buf * SHM_K + r32 * PITCH;
; #pragma unroll
;             for (int d0 = 0; d0 < ND; ++d0) {
;                 const LAS char* a = kbase + (((d0 * 32 + hi * 16) ^ ((r32 & 7) << 4)));
	s_or_saveexec_b64 s[10:11], s[12:13]
	v_mov_b64_e32 v[10:11], 0x4c000
	s_xor_b64 exec, exec, s[10:11]
	v_lshlrev_b64 v[8:9], 11, v[12:13]
	v_lshl_add_u64 v[8:9], s[0:1], 0, v[8:9]
	v_ashrrev_i32_e32 v11, 31, v0
	v_mov_b32_e32 v10, v0
	v_lshl_add_u64 v[8:9], v[10:11], 1, v[8:9]
	v_mov_b64_e32 v[10:11], 0x10000
	s_or_b64 exec, exec, s[10:11]
	s_add_u32 s0, s0, 0x100
	s_addc_u32 s1, s1, 0
	s_lshl_b32 s5, s5, 11
	s_ashr_i32 s10, s5, 8
	v_lshrrev_b32_e32 v0, 1, v16
	v_bfe_u32 v11, v16, 2, 2
	s_and_b32 s12, s10, -16
	v_and_b32_e32 v22, 8, v0
	s_lshr_b32 s10, s10, 1
	s_and_b32 s13, s10, 4
	v_or3_b32 v0, v22, v11, s12
	v_or_b32_e32 v12, s13, v0
	s_add_i32 s2, s2, 0
	v_lshlrev_b32_e32 v7, 3, v17
	v_and_b32_e32 v0, 32, v16
	v_ashrrev_i32_e32 v13, 31, v12
	s_add_i32 m0, s2, 0x8000
	v_and_or_b32 v0, v7, 24, v0
	v_lshlrev_b64 v[12:13], 11, v[12:13]
	global_load_lds_dwordx4 v[2:3], off
	s_add_i32 m0, s2, 0x8400
	v_lshl_add_u64 v[12:13], s[0:1], 0, v[12:13]
	v_lshlrev_b32_e32 v0, 1, v0
	global_load_lds_dwordx4 v[4:5], off
	s_add_i32 m0, s2, 0x8800
	s_add_i32 s78, s5, 0
	v_lshl_add_u64 v[12:13], v[12:13], 0, v[0:1]
	global_load_lds_dwordx4 v[8:9], off
	s_mov_b32 m0, s78
	v_lshl_add_u64 v[20:21], v[12:13], 0, s[96:97]
	global_load_lds_dwordx4 v[12:13], off
	s_add_i32 m0, s78, 0x400
	s_movk_i32 s5, 0x180
	global_load_lds_dwordx4 v[20:21], off
	v_mad_u32_u24 v166, v14, s5, 0
	v_lshlrev_b32_e32 v239, 3, v16
	v_lshlrev_b32_e32 v16, 4, v16
	s_movk_i32 s5, 0x70
	v_and_b32_e32 v13, 0xc0, v18
	v_and_b32_e32 v18, 0x70, v239
	v_bitop3_b32 v167, v152, v239, s5 bitop3:0x78
	s_movk_i32 s5, 0x60
	v_bitop3_b32 v170, v152, v18, s5 bitop3:0x36
	s_movk_i32 s5, 0x80
	v_bitop3_b32 v171, v152, v18, s5 bitop3:0x36
	s_movk_i32 s5, 0xa0
	v_bitop3_b32 v172, v152, v18, s5 bitop3:0x36
	s_movk_i32 s5, 0xc0
	v_bitop3_b32 v173, v152, v18, s5 bitop3:0x36
	s_movk_i32 s5, 0xe0
	v_bitop3_b32 v174, v152, v18, s5 bitop3:0x36
	s_movk_i32 s5, 0x100
	v_bitop3_b32 v175, v152, v18, s5 bitop3:0x36
	s_movk_i32 s5, 0x120
	v_bitop3_b32 v176, v152, v18, s5 bitop3:0x36
	s_movk_i32 s5, 0x140
	v_lshlrev_b32_e32 v12, 1, v17
	v_bitop3_b32 v177, v152, v18, s5 bitop3:0x36
	s_movk_i32 s5, 0x160
	v_and_b32_e32 v12, 32, v12
	v_bitop3_b32 v178, v152, v18, s5 bitop3:0x36
	s_movk_i32 s5, 0x118
	v_and_or_b32 v7, v7, s5, v12
	v_add3_u32 v179, v13, 0, v7
	v_or_b32_e32 v7, s12, v22
	v_or3_b32 v12, v7, s13, v11
	v_ashrrev_i32_e32 v13, 31, v12
	v_lshlrev_b64 v[12:13], 11, v[12:13]
	v_or_b32_e32 v12, v12, v0
	s_and_b32 s4, s4, 0x3fffffc0
	v_lshl_add_u64 v[12:13], s[0:1], 0, v[12:13]
	s_mov_b64 s[0:1], 0x20080
	s_lshl_b32 s4, s4, 2
	v_lshl_add_u64 v[154:155], v[12:13], 0, s[0:1]
	v_readlane_b32 s0, v255, 52
	v_readlane_b32 s1, v255, 53
	s_add_i32 s4, s4, 0
	v_lshlrev_b32_e32 v162, 1, v19
	v_mov_b32_e32 v163, v1
	s_add_i32 s0, s0, s1
	s_add_i32 s4, s4, 0x14200
	s_waitcnt vmcnt(0) lgkmcnt(0)
	s_barrier
	v_lshlrev_b32_e32 v15, 2, v15
	v_lshlrev_b32_e32 v0, 1, v10
	v_lshlrev_b32_e32 v158, 1, v6
	v_mov_b32_e32 v159, v1
	v_lshl_add_u64 v[164:165], v[2:3], 0, v[162:163]
	v_add_u32_e32 v2, s0, v14
	v_mov_b32_e32 v34, v1
	v_mov_b32_e32 v35, v1
	v_mov_b32_e32 v48, v1
	v_mov_b32_e32 v49, v1
	v_cmp_gt_u32_e64 s[10:11], 32, v17
	v_lshl_add_u32 v153, v14, 2, s4
	v_bitop3_b32 v168, v152, v18, 32 bitop3:0x36
	v_bitop3_b32 v169, v152, v18, 64 bitop3:0x36
	v_lshl_add_u64 v[156:157], v[8:9], 0, v[0:1]
	v_lshl_add_u64 v[160:161], v[4:5], 0, v[158:159]
	v_sub_u32_e32 v180, v2, v15
	v_mov_b32_e32 v36, v1
	v_mov_b32_e32 v37, v1
	v_mov_b32_e32 v38, v1
	v_mov_b32_e32 v39, v1
	v_mov_b32_e32 v40, v1
	v_mov_b32_e32 v41, v1
	v_mov_b32_e32 v42, v1
	v_mov_b32_e32 v43, v1
	v_mov_b32_e32 v44, v1
	v_mov_b32_e32 v45, v1
	v_mov_b32_e32 v46, v1
	v_mov_b32_e32 v47, v1
	v_mov_b64_e32 v[64:65], v[48:49]
	v_mov_b64_e32 v[18:19], v[34:35]
	v_mov_b64_e32 v[2:3], v[34:35]
	s_or_b32 s79, s6, 31
	s_mov_b32 s43, 0
	v_mov_b32_e32 v181, 0
	v_mov_b32_e32 v183, 0xf149f2ca
	s_mov_b32 s82, 63
	v_mov_b64_e32 v[62:63], v[46:47]
	v_mov_b64_e32 v[60:61], v[44:45]
	v_mov_b64_e32 v[58:59], v[42:43]
	v_mov_b64_e32 v[56:57], v[40:41]
	v_mov_b64_e32 v[54:55], v[38:39]
	v_mov_b64_e32 v[52:53], v[36:37]
	v_mov_b64_e32 v[50:51], v[34:35]
	v_mov_b64_e32 v[20:21], v[36:37]
	v_mov_b64_e32 v[22:23], v[38:39]
	v_mov_b64_e32 v[24:25], v[40:41]
	v_mov_b64_e32 v[26:27], v[42:43]
	v_mov_b64_e32 v[28:29], v[44:45]
	v_mov_b64_e32 v[30:31], v[46:47]
	v_mov_b64_e32 v[32:33], v[48:49]
	v_mov_b64_e32 v[4:5], v[36:37]
	v_mov_b64_e32 v[6:7], v[38:39]
	v_mov_b64_e32 v[8:9], v[40:41]
	v_mov_b64_e32 v[10:11], v[42:43]
	v_mov_b64_e32 v[12:13], v[44:45]
	v_mov_b64_e32 v[14:15], v[46:47]
	v_mov_b64_e32 v[16:17], v[48:49]
	s_and_b32 s5, s43, 1
	s_add_i32 s43, s43, 1
	s_cmp_ge_u32 s43, s7
	s_cbranch_scc1 .LBB0_1186
